# select: items after each workgroup's first handed out longest-first through a ticket counter instead of the static round order
# baseline (speedup 1.0000x reference)
; #define LAS __attribute__((address_space(3)))
; __device__ __forceinline__ void select_phase(const bf16_t* Z, const bf16_t* KIb, unsigned* MASKb, unsigned* itemcnt, LAS unsigned char* lds, int wave_in, int lane_in, int bid, int G, int sub) {
;     constexpr int SCS = 2312;
;     LAS float* sc = (LAS float*)lds;
;     const int nrounds = (1024 + G - 1) / G;
;     bf16x8 qf[4][2]; u32x2 wraw;
;     ...
;     { const int r0 = nrounds - 1; int i0_ = r0 * G + ((r0 & 1) ? (G - 1 - bid) : bid); SEL_LOADQ(i0_); }
.LBB0_112:
	s_mov_b32 s100, -1
	s_abs_i32 s4, s97
	v_cvt_f32_u32_e32 v0, s4
	s_add_i32 s5, s97, 0x3ff
	s_sub_i32 s6, 0xfffffc01, s97
	s_xor_b32 s7, s5, s97
	v_rcp_iflag_f32_e32 v0, v0
	s_max_i32 s5, s5, s6
	s_sub_i32 s6, 0, s4
	s_ashr_i32 s7, s7, 31
	v_mul_f32_e32 v0, 0x4f7ffffe, v0
	v_cvt_u32_f32_e32 v0, v0
	v_and_b32_e32 v135, 15, v166
	v_readlane_b32 s38, v255, 11
	v_readlane_b32 s39, v255, 12
	v_readfirstlane_b32 s8, v0
	s_mul_i32 s6, s6, s8
	s_mul_hi_u32 s6, s8, s6
	s_add_i32 s8, s8, s6
	s_mul_hi_u32 s6, s5, s8
	s_mul_i32 s8, s6, s4
	s_sub_i32 s5, s5, s8
	s_add_i32 s9, s6, 1
	s_sub_i32 s8, s5, s4
	s_cmp_ge_u32 s5, s4
	s_cselect_b32 s6, s9, s6
	s_cselect_b32 s5, s8, s5
	s_add_i32 s8, s6, 1
	s_cmp_ge_u32 s5, s4
	s_cselect_b32 s4, s8, s6
	s_xor_b32 s4, s4, s7
	s_sub_i32 s77, s4, s7
	s_cmp_lt_i32 s77, 1
	s_cbranch_scc1 .LBB0_243
	v_readlane_b32 s4, v255, 28
	v_readlane_b32 s5, v255, 29
	s_lshl_b32 s4, s4, 10
	s_ashr_i32 s5, s4, 31
	s_lshl_b64 s[4:5], s[4:5], 2
	s_add_u32 s4, s78, s4
	s_addc_u32 s5, s79, s5
	s_add_u32 s80, s4, 0xfa08000
	s_addc_u32 s84, s5, 0
	s_not_b32 s4, s76
	s_add_i32 s86, s77, -1
	s_add_i32 s87, s97, s4
	s_bitcmp0_b32 s86, 0
	s_cselect_b32 s4, s76, s87
	s_mul_i32 s5, s86, s97
	s_add_i32 s4, s4, s5
	s_min_i32 s4, s4, 0x3ff
	s_lshl_b32 s5, s4, 12
	s_lshl_b32 s4, s4, 2
	s_and_b32 s4, s4, -16
	s_and_b32 s5, s5, 0x3000
	s_ashr_i32 s6, s4, 31
	v_ashrrev_i32_e32 v0, 1, v166
	s_add_u32 s4, s5, s4
	s_waitcnt vmcnt(2)
	v_and_b32_e32 v66, -8, v0
	v_or_b32_e32 v0, s4, v135
	v_mov_b64_e32 v[2:3], s[0:1]
	s_addc_u32 s6, 0, s6
	v_mad_u64_u32 v[34:35], s[4:5], v0, s33, v[2:3]
	v_ashrrev_i32_e32 v67, 31, v66
	v_mad_i32_i24 v35, s6, v218, v35
	v_lshl_add_u64 v[26:27], v[66:67], 1, v[34:35]
	s_mov_b64 s[4:5], 0x1000
	v_lshl_add_u64 v[28:29], v[26:27], 0, s[4:5]
	s_movk_i32 s4, 0x1000
	global_load_dwordx4 v[2:5], v[28:29], off offset:384
	global_load_dwordx4 v[6:9], v[28:29], off offset:320
	global_load_dwordx4 v[10:13], v[28:29], off offset:256
	global_load_dwordx4 v[14:17], v[28:29], off offset:192
	global_load_dwordx4 v[18:21], v[28:29], off offset:128
	global_load_dwordx4 v[22:25], v[28:29], off offset:64
	s_waitcnt vmcnt(6)
	v_add_co_u32_e32 v30, vcc, s4, v26
	v_and_b32_e32 v0, 64, v179
	s_nop 0
	v_addc_co_u32_e32 v31, vcc, 0, v27, vcc
	v_add_co_u32_e32 v34, vcc, s4, v34
	global_load_dwordx4 v[26:29], v[28:29], off offset:448
	s_nop 0
	global_load_dwordx4 v[30:33], v[30:31], off
	v_addc_co_u32_e32 v35, vcc, 0, v35, vcc
	global_load_dwordx2 v[70:71], v[34:35], off offset:1664
	v_add_u32_e32 v34, -1, v179
	v_cmp_lt_i32_e32 vcc, v34, v0
	s_mov_b32 s88, 0
	s_nop 0
	v_cndmask_b32_e32 v34, v34, v179, vcc
	v_lshlrev_b32_e32 v100, 2, v34
	v_add_u32_e32 v34, -2, v179
	v_cmp_lt_i32_e32 vcc, v34, v0
	s_nop 1
	v_cndmask_b32_e32 v34, v34, v179, vcc
	v_lshlrev_b32_e32 v101, 2, v34
	v_add_u32_e32 v34, -4, v179
	v_cmp_lt_i32_e32 vcc, v34, v0
	s_nop 1
	v_cndmask_b32_e32 v34, v34, v179, vcc
	v_lshlrev_b32_e32 v102, 2, v34
	v_add_u32_e32 v34, -8, v179
	v_cmp_lt_i32_e32 vcc, v34, v0
	s_nop 1
	v_cndmask_b32_e32 v34, v34, v179, vcc
	v_lshlrev_b32_e32 v103, 2, v34
	v_add_u32_e32 v34, -16, v179
	v_cmp_lt_i32_e32 vcc, v34, v0
	s_nop 1
	v_cndmask_b32_e32 v34, v34, v179, vcc
	v_lshlrev_b32_e32 v104, 2, v34
	v_subrev_u32_e32 v34, 32, v179
	v_cmp_lt_i32_e32 vcc, v34, v0
	s_nop 1
	v_cndmask_b32_e32 v0, v34, v179, vcc
	v_lshlrev_b32_e32 v105, 2, v0
	s_add_i32 s99, s87, 0x300
	s_movk_i32 s98, 0x7fff
	s_branch .LBB0_116

; __device__ __forceinline__ void select_phase(const bf16_t* Z, const bf16_t* KIb, unsigned* MASKb, unsigned* itemcnt, LAS unsigned char* lds, int wave_in, int lane_in, int bid, int G, int sub) {
;     ...
;     for (int rd = 0; rd < nrounds; ++rd) {
;         const int rr_ = nrounds - 1 - rd, rn_ = rr_ > 0 ? rr_ - 1 : 0;
;         const int idx = rr_ * G + ((rr_ & 1) ? (G - 1 - bid) : bid);
;         const int idxn = rn_ * G + ((rn_ & 1) ? (G - 1 - bid) : bid);
;         if (idx >= 1024) continue;
;         const int b = idx & 3, q0 = (idx >> 2) * 16;
;         int wave = wave_in, lane = lane_in; asm volatile("" : "+s"(wave), "+v"(lane));
;         const int fr = lane & 15, fq = lane >> 4;
.LBB0_115:
	s_mov_b32 s99, s98
	s_movk_i32 s98, 0x7fff
	s_cmpk_lt_i32 s99, 0x400
	s_cbranch_scc0 .LBB0_243
.LBB0_116:
	v_readlane_b32 s4, v255, 21
	s_cmp_lg_u32 s4, 0
	s_cbranch_scc1 .Ldy_skip
	v_readlane_b32 s4, v255, 28
	s_lshl_b32 s4, s4, 2
	s_add_u32 s4, s78, s4
	s_addc_u32 s5, s79, 0
	s_add_u32 s4, s4, 0xfa036b0
	s_addc_u32 s5, s5, 0
	v_mov_b32_e32 v139, 1
	s_mov_b64 vcc, exec
	s_mov_b64 exec, 1
	global_atomic_add v138, v1, v139, s[4:5] sc0
	s_mov_b64 exec, vcc
.Ldy_skip:
	s_mov_b32 s74, s99
	s_mov_b32 s7, s74
	s_lshl_b32 s4, s74, 2
	s_ashr_i32 s8, s74, 2
	s_and_b32 s20, s74, 3
	s_and_b32 s9, s4, -16
	s_add_i32 s4, s8, 0x80
	v_mov_b32_e32 v68, v166
	v_readlane_b32 s6, v255, 21
	s_ashr_i32 s10, s4, 7
	s_lshl_b32 s4, s20, 19
	v_readlane_b32 s12, v255, 36
	v_readlane_b32 s13, v255, 37
	v_and_b32_e32 v38, 15, v68
	s_add_u32 s4, s12, s4
	s_addc_u32 s5, s13, 0
	v_lshlrev_b32_e32 v0, 6, v38
	v_lshl_add_u64 v[34:35], s[4:5], 0, v[0:1]
	s_movk_i32 s4, 0x2420
	v_mad_u32_u24 v69, v38, s4, 0
	s_min_i32 s4, s7, 0x3ff
	s_lshl_b32 s5, s4, 12
	s_lshl_b32 s4, s4, 2
	v_ashrrev_i32_e32 v0, 1, v68
	s_lshl_b32 s75, s6, 1
	s_and_b32 s4, s4, -16
	v_and_b32_e32 v36, -8, v0
	s_add_i32 s75, s75, s9
	s_and_b32 s5, s5, 0x3000
	s_ashr_i32 s7, s4, 31
	v_ashrrev_i32_e32 v37, 31, v36
	s_add_u32 s4, s5, s4
	s_waitcnt vmcnt(11)
	v_lshl_add_u64 v[80:81], v[36:37], 1, v[34:35]
	v_or_b32_e32 v0, s4, v135
	v_mov_b64_e32 v[34:35], s[0:1]
	s_addc_u32 s7, 0, s7
	v_mad_u64_u32 v[34:35], s[4:5], v0, s33, v[34:35]
	v_mad_i32_i24 v35, s7, v218, v35
	v_lshl_add_u64 v[36:37], v[66:67], 1, v[34:35]
	s_mov_b64 s[4:5], 0x1000
	v_lshl_add_u64 v[82:83], v[36:37], 0, s[4:5]
	s_mov_b64 s[4:5], 0x1680
	v_lshl_add_u64 v[84:85], v[34:35], 0, s[4:5]
	s_mul_i32 s4, s6, 0x4840
	s_add_i32 s9, s4, 0
	s_movk_i32 s4, 0x90
	v_mov_b32_e32 v86, s6
	s_cmp_lt_i32 s100, 0
	s_cbranch_scc0 .Lsf_pend
	s_waitcnt vmcnt(0)
	s_branch .Lsf_cont

; __device__ __forceinline__ void select_phase(const bf16_t* Z, const bf16_t* KIb, unsigned* MASKb, unsigned* itemcnt, LAS unsigned char* lds, int wave_in, int lane_in, int bid, int G, int sub) {
;     ...
;                 __syncthreads();
;                 if (c + 1 == nch) SEL_LOADQ(idxn);
.Lsf_none:
	v_readlane_b32 s4, v255, 21
	s_cmp_lg_u32 s4, 0
	s_cbranch_scc1 .Ldy_nopub
	v_mov_b32_e32 v139, 0x24400
	s_mov_b64 vcc, exec
	s_mov_b64 exec, 1
	ds_write_b32 v139, v138
	s_mov_b64 exec, vcc
	s_waitcnt lgkmcnt(0)
.Ldy_nopub:
	s_barrier
	v_mov_b32_e32 v34, 0x24400
	ds_read_b32 v34, v34
	s_waitcnt lgkmcnt(0)
	v_readfirstlane_b32 s98, v34
	s_sub_i32 s98, 0x2ff, s98
	s_cmp_lt_i32 s98, 0
	s_cselect_b32 s98, 0x7fff, s98
	s_min_i32 s4, s98, 0x3ff
	s_lshl_b32 s5, s4, 12
	s_lshl_b32 s4, s4, 2
	s_and_b32 s4, s4, -16
	s_and_b32 s5, s5, 0x3000
	s_ashr_i32 s7, s4, 31
	s_add_u32 s4, s5, s4
	s_addc_u32 s7, 0, s7
	v_or_b32_e32 v34, s4, v135
	v_mov_b64_e32 v[36:37], s[0:1]
	v_mad_u64_u32 v[36:37], s[4:5], v34, s33, v[36:37]
	v_mad_i32_i24 v37, s7, v218, v37
	v_lshl_add_u64 v[38:39], v[66:67], 1, v[36:37]
	s_mov_b64 s[4:5], 0x1000
	v_lshl_add_u64 v[82:83], v[38:39], 0, s[4:5]
	s_mov_b64 s[4:5], 0x1680
	v_lshl_add_u64 v[84:85], v[36:37], 0, s[4:5]
	s_cmp_lg_u32 s10, 1
	s_cbranch_scc1 .LBB0_123
	global_load_dwordx4 v[30:33], v[82:83], off
	global_load_dwordx4 v[22:25], v[82:83], off offset:64
	global_load_dwordx4 v[18:21], v[82:83], off offset:128
	global_load_dwordx4 v[14:17], v[82:83], off offset:192
	global_load_dwordx4 v[10:13], v[82:83], off offset:256
	global_load_dwordx4 v[6:9], v[82:83], off offset:320
	global_load_dwordx4 v[2:5], v[82:83], off offset:384
	global_load_dwordx4 v[26:29], v[82:83], off offset:448
	global_load_dwordx2 v[70:71], v[84:85], off
